# v08 + P2 GEMM-side K-loop throttled with s_sleep 32 (GEMM half has slack; frees power/bandwidth for the scan chain)
# speedup vs baseline: 1.0272x; 1.0083x over previous
.LBB0_255:
	ds_read_b128 v[128:131], v182
	ds_read_b128 v[132:135], v182 offset:1024
	ds_read_b128 v[136:139], v182 offset:2048
	ds_read_b128 v[140:143], v182 offset:3072
	ds_read_b128 v[164:167], v183
	ds_read_b128 v[168:171], v183 offset:1024
	ds_read_b128 v[172:175], v183 offset:2048
	ds_read_b128 v[186:189], v183 offset:3072
	s_add_u32 s28, s0, 0xfffc0080
	s_addc_u32 s29, s1, -1
	s_cmp_eq_u32 s58, 12
	s_cselect_b32 s31, s23, s29
	s_cselect_b32 s30, s54, s28
	s_cselect_b32 s29, s21, s57
	s_cselect_b32 s28, s55, s56
	v_lshl_add_u64 v[176:177], s[0:1], 0, v[156:157]
	s_add_i32 m0, s39, 0xc000
	ds_read_b128 v[190:193], v184
	ds_read_b128 v[194:197], v184 offset:1024
	ds_read_b128 v[198:201], v184 offset:2048
	ds_read_b128 v[202:205], v184 offset:3072
	ds_read_b128 v[206:209], v184 offset:4096
	ds_read_b128 v[210:213], v184 offset:5120
	ds_read_b128 v[214:217], v184 offset:6144
	ds_read_b128 v[218:221], v184 offset:7168
	global_load_lds_dwordx4 v[176:177], off
	v_lshl_add_u64 v[176:177], s[0:1], 0, v[158:159]
	s_add_i32 m0, s39, 0xe000
	s_nop 0
	global_load_lds_dwordx4 v[176:177], off
	s_waitcnt vmcnt(8)
	s_waitcnt lgkmcnt(0)
	s_barrier
	s_setprio 1
	s_waitcnt lgkmcnt(0)
	v_mfma_f32_16x16x32_bf16 v[124:127], v[128:131], v[190:193], v[124:127]
	v_mfma_f32_16x16x32_bf16 v[120:123], v[136:139], v[190:193], v[120:123]
	v_mfma_f32_16x16x32_bf16 v[116:119], v[128:131], v[198:201], v[116:119]
	v_mfma_f32_16x16x32_bf16 v[108:111], v[136:139], v[198:201], v[108:111]
	v_mfma_f32_16x16x32_bf16 v[100:103], v[128:131], v[206:209], v[100:103]
	v_mfma_f32_16x16x32_bf16 v[92:95], v[136:139], v[206:209], v[92:95]
	v_mfma_f32_16x16x32_bf16 v[84:87], v[128:131], v[214:217], v[84:87]
	v_mfma_f32_16x16x32_bf16 v[76:79], v[136:139], v[214:217], v[76:79]
	v_mfma_f32_16x16x32_bf16 v[124:127], v[132:135], v[194:197], v[124:127]
	v_mfma_f32_16x16x32_bf16 v[120:123], v[140:143], v[194:197], v[120:123]
	v_mfma_f32_16x16x32_bf16 v[116:119], v[132:135], v[202:205], v[116:119]
	v_mfma_f32_16x16x32_bf16 v[108:111], v[140:143], v[202:205], v[108:111]
	v_mfma_f32_16x16x32_bf16 v[100:103], v[132:135], v[210:213], v[100:103]
	v_mfma_f32_16x16x32_bf16 v[92:95], v[140:143], v[210:213], v[92:95]
	v_mfma_f32_16x16x32_bf16 v[84:87], v[132:135], v[218:221], v[84:87]
	v_mfma_f32_16x16x32_bf16 v[76:79], v[140:143], v[218:221], v[76:79]
	s_setprio 0
	s_setprio 1
	v_mfma_f32_16x16x32_bf16 v[112:115], v[164:167], v[190:193], v[112:115]
	v_mfma_f32_16x16x32_bf16 v[104:107], v[172:175], v[190:193], v[104:107]
	v_mfma_f32_16x16x32_bf16 v[96:99], v[164:167], v[198:201], v[96:99]
	v_mfma_f32_16x16x32_bf16 v[88:91], v[172:175], v[198:201], v[88:91]
	v_mfma_f32_16x16x32_bf16 v[80:83], v[164:167], v[206:209], v[80:83]
	v_mfma_f32_16x16x32_bf16 v[72:75], v[172:175], v[206:209], v[72:75]
	v_mfma_f32_16x16x32_bf16 v[68:71], v[164:167], v[214:217], v[68:71]
	v_mfma_f32_16x16x32_bf16 v[64:67], v[172:175], v[214:217], v[64:67]
	v_mfma_f32_16x16x32_bf16 v[112:115], v[168:171], v[194:197], v[112:115]
	v_mfma_f32_16x16x32_bf16 v[104:107], v[186:189], v[194:197], v[104:107]
	v_mfma_f32_16x16x32_bf16 v[96:99], v[168:171], v[202:205], v[96:99]
	v_mfma_f32_16x16x32_bf16 v[88:91], v[186:189], v[202:205], v[88:91]
	v_mfma_f32_16x16x32_bf16 v[80:83], v[168:171], v[210:213], v[80:83]
	v_mfma_f32_16x16x32_bf16 v[72:75], v[186:189], v[210:213], v[72:75]
	v_mfma_f32_16x16x32_bf16 v[68:71], v[168:171], v[218:221], v[68:71]
	v_mfma_f32_16x16x32_bf16 v[64:67], v[186:189], v[218:221], v[64:67]
	s_setprio 0
	s_barrier
	s_add_i32 s59, s47, s38
	v_lshl_add_u64 v[176:177], s[28:29], 0, v[148:149]
	s_mov_b32 m0, s59
	ds_read_b128 v[190:193], v184 offset:16384
	ds_read_b128 v[194:197], v184 offset:17408
	ds_read_b128 v[198:201], v184 offset:18432
	ds_read_b128 v[202:205], v184 offset:19456
	ds_read_b128 v[206:209], v184 offset:20480
	ds_read_b128 v[210:213], v184 offset:21504
	ds_read_b128 v[214:217], v184 offset:22528
	ds_read_b128 v[218:221], v184 offset:23552
	global_load_lds_dwordx4 v[176:177], off
	s_add_i32 m0, s59, 0x2000
	s_add_u32 s60, s28, 0x40000
	v_lshl_add_u64 v[222:223], s[28:29], 0, v[144:145]
	s_addc_u32 s61, s29, 0
	s_add_i32 s59, s48, s38
	global_load_lds_dwordx4 v[222:223], off
	v_lshl_add_u64 v[224:225], s[60:61], 0, v[148:149]
	s_mov_b32 m0, s59
	v_lshl_add_u64 v[226:227], s[30:31], 0, v[146:147]
	global_load_lds_dwordx4 v[224:225], off
	v_lshl_add_u64 v[224:225], s[60:61], 0, v[144:145]
	s_add_i32 m0, s59, 0x2000
	s_nop 0
	global_load_lds_dwordx4 v[224:225], off
	v_lshl_add_u64 v[224:225], s[30:31], 0, v[150:151]
	s_mov_b32 m0, s39
	s_nop 0
	global_load_lds_dwordx4 v[224:225], off
	s_mov_b32 m0, s40
	s_nop 0
	global_load_lds_dwordx4 v[226:227], off
	s_waitcnt vmcnt(8)
	s_waitcnt lgkmcnt(0)
	s_barrier
	s_setprio 1
	s_waitcnt lgkmcnt(0)
	v_mfma_f32_16x16x32_bf16 v[60:63], v[128:131], v[190:193], v[60:63]
	v_mfma_f32_16x16x32_bf16 v[56:59], v[136:139], v[190:193], v[56:59]
	v_mfma_f32_16x16x32_bf16 v[52:55], v[128:131], v[198:201], v[52:55]
	v_mfma_f32_16x16x32_bf16 v[44:47], v[136:139], v[198:201], v[44:47]
	v_mfma_f32_16x16x32_bf16 v[36:39], v[128:131], v[206:209], v[36:39]
	v_mfma_f32_16x16x32_bf16 v[28:31], v[136:139], v[206:209], v[28:31]
	v_mfma_f32_16x16x32_bf16 v[20:23], v[128:131], v[214:217], v[20:23]
	v_mfma_f32_16x16x32_bf16 v[12:15], v[136:139], v[214:217], v[12:15]
	v_mfma_f32_16x16x32_bf16 v[60:63], v[132:135], v[194:197], v[60:63]
	v_mfma_f32_16x16x32_bf16 v[56:59], v[140:143], v[194:197], v[56:59]
	v_mfma_f32_16x16x32_bf16 v[52:55], v[132:135], v[202:205], v[52:55]
	v_mfma_f32_16x16x32_bf16 v[44:47], v[140:143], v[202:205], v[44:47]
	v_mfma_f32_16x16x32_bf16 v[36:39], v[132:135], v[210:213], v[36:39]
	v_mfma_f32_16x16x32_bf16 v[28:31], v[140:143], v[210:213], v[28:31]
	v_mfma_f32_16x16x32_bf16 v[20:23], v[132:135], v[218:221], v[20:23]
	v_mfma_f32_16x16x32_bf16 v[12:15], v[140:143], v[218:221], v[12:15]
	s_setprio 0
	s_setprio 1
	v_mfma_f32_16x16x32_bf16 v[48:51], v[164:167], v[190:193], v[48:51]
	v_mfma_f32_16x16x32_bf16 v[40:43], v[172:175], v[190:193], v[40:43]
	v_mfma_f32_16x16x32_bf16 v[32:35], v[164:167], v[198:201], v[32:35]
	v_mfma_f32_16x16x32_bf16 v[24:27], v[172:175], v[198:201], v[24:27]
	v_mfma_f32_16x16x32_bf16 v[16:19], v[164:167], v[206:209], v[16:19]
	v_mfma_f32_16x16x32_bf16 v[8:11], v[172:175], v[206:209], v[8:11]
	v_mfma_f32_16x16x32_bf16 v[4:7], v[164:167], v[214:217], v[4:7]
	v_mfma_f32_16x16x32_bf16 v[0:3], v[172:175], v[214:217], v[0:3]
	v_mfma_f32_16x16x32_bf16 v[48:51], v[168:171], v[194:197], v[48:51]
	v_mfma_f32_16x16x32_bf16 v[40:43], v[186:189], v[194:197], v[40:43]
	v_mfma_f32_16x16x32_bf16 v[32:35], v[168:171], v[202:205], v[32:35]
	v_mfma_f32_16x16x32_bf16 v[24:27], v[186:189], v[202:205], v[24:27]
	v_mfma_f32_16x16x32_bf16 v[16:19], v[168:171], v[210:213], v[16:19]
	v_mfma_f32_16x16x32_bf16 v[8:11], v[186:189], v[210:213], v[8:11]
	v_mfma_f32_16x16x32_bf16 v[4:7], v[168:171], v[218:221], v[4:7]
	v_mfma_f32_16x16x32_bf16 v[0:3], v[186:189], v[218:221], v[0:3]
	s_setprio 0
	s_barrier
	s_add_i32 s59, 0, 0x18000
	s_add_i32 s60, 0, 0x1c000
	v_add_u32_e32 v140, s59, v180
	v_add_u32_e32 v152, s60, v180
	ds_read_b128 v[128:131], v140
	ds_read_b128 v[132:135], v140 offset:1024
	ds_read_b128 v[136:139], v140 offset:2048
	ds_read_b128 v[140:143], v140 offset:3072
	ds_read_b128 v[164:167], v152
	ds_read_b128 v[168:171], v152 offset:1024
	ds_read_b128 v[172:175], v152 offset:2048
	ds_read_b128 v[186:189], v152 offset:3072
	s_add_u32 s30, s30, 0x40000
	s_addc_u32 s31, s31, 0
	s_mov_b32 m0, s41
	v_lshl_add_u64 v[228:229], s[30:31], 0, v[150:151]
	ds_read_b128 v[190:193], v184 offset:32768
	ds_read_b128 v[194:197], v184 offset:33792
	ds_read_b128 v[198:201], v184 offset:34816
	ds_read_b128 v[202:205], v184 offset:35840
	ds_read_b128 v[206:209], v184 offset:36864
	ds_read_b128 v[210:213], v184 offset:37888
	ds_read_b128 v[214:217], v184 offset:38912
	ds_read_b128 v[218:221], v184 offset:39936
	global_load_lds_dwordx4 v[228:229], off
	v_lshl_add_u64 v[228:229], s[30:31], 0, v[146:147]
	s_mov_b32 m0, s42
	s_nop 0
	global_load_lds_dwordx4 v[228:229], off
	s_waitcnt vmcnt(8)
	s_waitcnt lgkmcnt(0)
	s_barrier
	s_setprio 1
	s_waitcnt lgkmcnt(0)
	v_mfma_f32_16x16x32_bf16 v[124:127], v[128:131], v[190:193], v[124:127]
	v_mfma_f32_16x16x32_bf16 v[120:123], v[136:139], v[190:193], v[120:123]
	v_mfma_f32_16x16x32_bf16 v[116:119], v[128:131], v[198:201], v[116:119]
	v_mfma_f32_16x16x32_bf16 v[108:111], v[136:139], v[198:201], v[108:111]
	v_mfma_f32_16x16x32_bf16 v[100:103], v[128:131], v[206:209], v[100:103]
	v_mfma_f32_16x16x32_bf16 v[92:95], v[136:139], v[206:209], v[92:95]
	v_mfma_f32_16x16x32_bf16 v[84:87], v[128:131], v[214:217], v[84:87]
	v_mfma_f32_16x16x32_bf16 v[76:79], v[136:139], v[214:217], v[76:79]
	v_mfma_f32_16x16x32_bf16 v[124:127], v[132:135], v[194:197], v[124:127]
	v_mfma_f32_16x16x32_bf16 v[120:123], v[140:143], v[194:197], v[120:123]
	v_mfma_f32_16x16x32_bf16 v[116:119], v[132:135], v[202:205], v[116:119]
	v_mfma_f32_16x16x32_bf16 v[108:111], v[140:143], v[202:205], v[108:111]
	v_mfma_f32_16x16x32_bf16 v[100:103], v[132:135], v[210:213], v[100:103]
	v_mfma_f32_16x16x32_bf16 v[92:95], v[140:143], v[210:213], v[92:95]
	v_mfma_f32_16x16x32_bf16 v[84:87], v[132:135], v[218:221], v[84:87]
	v_mfma_f32_16x16x32_bf16 v[76:79], v[140:143], v[218:221], v[76:79]
	s_setprio 0
	s_setprio 1
	v_mfma_f32_16x16x32_bf16 v[112:115], v[164:167], v[190:193], v[112:115]
	v_mfma_f32_16x16x32_bf16 v[104:107], v[172:175], v[190:193], v[104:107]
	v_mfma_f32_16x16x32_bf16 v[96:99], v[164:167], v[198:201], v[96:99]
	v_mfma_f32_16x16x32_bf16 v[88:91], v[172:175], v[198:201], v[88:91]
	v_mfma_f32_16x16x32_bf16 v[80:83], v[164:167], v[206:209], v[80:83]
	v_mfma_f32_16x16x32_bf16 v[72:75], v[172:175], v[206:209], v[72:75]
	v_mfma_f32_16x16x32_bf16 v[68:71], v[164:167], v[214:217], v[68:71]
	v_mfma_f32_16x16x32_bf16 v[64:67], v[172:175], v[214:217], v[64:67]
	v_mfma_f32_16x16x32_bf16 v[112:115], v[168:171], v[194:197], v[112:115]
	v_mfma_f32_16x16x32_bf16 v[104:107], v[186:189], v[194:197], v[104:107]
	v_mfma_f32_16x16x32_bf16 v[96:99], v[168:171], v[202:205], v[96:99]
	v_mfma_f32_16x16x32_bf16 v[88:91], v[186:189], v[202:205], v[88:91]
	v_mfma_f32_16x16x32_bf16 v[80:83], v[168:171], v[210:213], v[80:83]
	v_mfma_f32_16x16x32_bf16 v[72:75], v[186:189], v[210:213], v[72:75]
	v_mfma_f32_16x16x32_bf16 v[68:71], v[168:171], v[218:221], v[68:71]
	v_mfma_f32_16x16x32_bf16 v[64:67], v[186:189], v[218:221], v[64:67]
	s_setprio 0
	s_barrier
	s_add_i32 s30, s59, s38
	v_lshl_add_u64 v[176:177], v[176:177], 0, s[10:11]
	s_mov_b32 m0, s30
	ds_read_b128 v[190:193], v184 offset:49152
	ds_read_b128 v[194:197], v184 offset:50176
	ds_read_b128 v[198:201], v184 offset:51200
	ds_read_b128 v[202:205], v184 offset:52224
	ds_read_b128 v[206:209], v184 offset:53248
	ds_read_b128 v[210:213], v184 offset:54272
	ds_read_b128 v[214:217], v184 offset:55296
	ds_read_b128 v[218:221], v184 offset:56320
	global_load_lds_dwordx4 v[176:177], off
	s_add_i32 m0, s30, 0x2000
	s_add_u32 s28, s28, 0x40080
	v_lshl_add_u64 v[176:177], v[222:223], 0, s[10:11]
	s_addc_u32 s29, s29, 0
	s_add_i32 s30, s60, s38
	global_load_lds_dwordx4 v[176:177], off
	v_lshl_add_u64 v[176:177], s[28:29], 0, v[148:149]
	s_mov_b32 m0, s30
	s_nop 0
	global_load_lds_dwordx4 v[176:177], off
	v_lshl_add_u64 v[176:177], s[28:29], 0, v[144:145]
	s_add_i32 m0, s30, 0x2000
	s_nop 0
	global_load_lds_dwordx4 v[176:177], off
	v_lshl_add_u64 v[176:177], v[224:225], 0, s[10:11]
	s_mov_b32 m0, s44
	s_nop 0
	global_load_lds_dwordx4 v[176:177], off
	v_lshl_add_u64 v[176:177], v[226:227], 0, s[10:11]
	s_mov_b32 m0, s45
	s_nop 0
	global_load_lds_dwordx4 v[176:177], off
	s_waitcnt vmcnt(8)
	s_waitcnt lgkmcnt(0)
	s_barrier
	s_setprio 1
	s_waitcnt lgkmcnt(0)
	v_mfma_f32_16x16x32_bf16 v[60:63], v[128:131], v[190:193], v[60:63]
	v_mfma_f32_16x16x32_bf16 v[56:59], v[136:139], v[190:193], v[56:59]
	v_mfma_f32_16x16x32_bf16 v[52:55], v[128:131], v[198:201], v[52:55]
	v_mfma_f32_16x16x32_bf16 v[44:47], v[136:139], v[198:201], v[44:47]
	v_mfma_f32_16x16x32_bf16 v[36:39], v[128:131], v[206:209], v[36:39]
	v_mfma_f32_16x16x32_bf16 v[28:31], v[136:139], v[206:209], v[28:31]
	v_mfma_f32_16x16x32_bf16 v[20:23], v[128:131], v[214:217], v[20:23]
	v_mfma_f32_16x16x32_bf16 v[12:15], v[136:139], v[214:217], v[12:15]
	v_mfma_f32_16x16x32_bf16 v[60:63], v[132:135], v[194:197], v[60:63]
	v_mfma_f32_16x16x32_bf16 v[56:59], v[140:143], v[194:197], v[56:59]
	v_mfma_f32_16x16x32_bf16 v[52:55], v[132:135], v[202:205], v[52:55]
	v_mfma_f32_16x16x32_bf16 v[44:47], v[140:143], v[202:205], v[44:47]
	v_mfma_f32_16x16x32_bf16 v[36:39], v[132:135], v[210:213], v[36:39]
	v_mfma_f32_16x16x32_bf16 v[28:31], v[140:143], v[210:213], v[28:31]
	v_mfma_f32_16x16x32_bf16 v[20:23], v[132:135], v[218:221], v[20:23]
	v_mfma_f32_16x16x32_bf16 v[12:15], v[140:143], v[218:221], v[12:15]
	s_setprio 0
	s_setprio 1
	v_mfma_f32_16x16x32_bf16 v[48:51], v[164:167], v[190:193], v[48:51]
	v_mfma_f32_16x16x32_bf16 v[40:43], v[172:175], v[190:193], v[40:43]
	v_mfma_f32_16x16x32_bf16 v[32:35], v[164:167], v[198:201], v[32:35]
	v_mfma_f32_16x16x32_bf16 v[24:27], v[172:175], v[198:201], v[24:27]
	v_mfma_f32_16x16x32_bf16 v[16:19], v[164:167], v[206:209], v[16:19]
	v_mfma_f32_16x16x32_bf16 v[8:11], v[172:175], v[206:209], v[8:11]
	v_mfma_f32_16x16x32_bf16 v[4:7], v[164:167], v[214:217], v[4:7]
	v_mfma_f32_16x16x32_bf16 v[0:3], v[172:175], v[214:217], v[0:3]
	v_mfma_f32_16x16x32_bf16 v[48:51], v[168:171], v[194:197], v[48:51]
	v_mfma_f32_16x16x32_bf16 v[40:43], v[186:189], v[194:197], v[40:43]
	v_mfma_f32_16x16x32_bf16 v[32:35], v[168:171], v[202:205], v[32:35]
	v_mfma_f32_16x16x32_bf16 v[24:27], v[186:189], v[202:205], v[24:27]
	v_mfma_f32_16x16x32_bf16 v[16:19], v[168:171], v[210:213], v[16:19]
	v_mfma_f32_16x16x32_bf16 v[8:11], v[186:189], v[210:213], v[8:11]
	v_mfma_f32_16x16x32_bf16 v[4:7], v[168:171], v[218:221], v[4:7]
	v_mfma_f32_16x16x32_bf16 v[0:3], v[186:189], v[218:221], v[0:3]
	s_setprio 0
	s_barrier
	s_add_i32 s58, s58, 2
	s_add_u32 s0, s0, 0x100
	s_addc_u32 s1, s1, 0
	s_add_u32 s56, s56, 0x100
	s_addc_u32 s57, s57, 0
	s_cmp_gt_u32 s58, 13
	s_sleep 32
	s_cbranch_scc0 .LBB0_255
	s_and_b64 vcc, exec, s[12:13]
	s_cbranch_vccz .LBB0_258
	s_barrier

.LBB0_380:
	s_or_b64 exec, exec, s[94:95]
	s_add_i32 s14, s15, 1
	s_cmp_lt_u32 s14, s0
	s_cselect_b32 s15, s14, s15
	s_lshl_b32 s16, s15, 6
	v_add_u32_e32 v2, s13, v231
	s_add_i32 s16, s16, s97
	v_ashrrev_i32_e32 v3, 31, v2
	s_cmp_eq_u32 s15, 0
	v_lshlrev_b64 v[2:3], 12, v[2:3]
	s_cselect_b32 s15, 0, 0x1000
	v_lshl_add_u64 v[190:191], v[164:165], 0, v[2:3]
	v_add_u32_e32 v2, s16, v1
	v_mov_b32_e32 v84, s15
	v_ashrrev_i32_e32 v3, 31, v2
	v_cndmask_b32_e64 v86, v84, v195, s[6:7]
	v_lshlrev_b64 v[2:3], 13, v[2:3]
	v_mul_u32_u24_e32 v84, 3, v86
	v_lshl_add_u64 v[2:3], v[176:177], 0, v[2:3]
	v_lshlrev_b32_e32 v84, 1, v84
	v_sub_co_u32_e32 v84, vcc, v2, v84
	global_load_dwordx4 v[76:79], v[190:191], off
	global_load_dwordx4 v[80:83], v[190:191], off offset:128
	global_load_dwordx4 v[72:75], v[190:191], off offset:256
	global_load_dwordx4 v[68:71], v[190:191], off offset:384
	s_waitcnt lgkmcnt(0)
	s_barrier
	v_subbrev_co_u32_e32 v85, vcc, 0, v3, vcc
	global_load_dword v250, v[84:85], off
	v_lshlrev_b32_e32 v84, 2, v86
	v_sub_co_u32_e32 v84, vcc, v2, v84
	v_lshlrev_b32_e32 v87, 1, v86
	s_nop 0
	v_subbrev_co_u32_e32 v85, vcc, 0, v3, vcc
	global_load_dword v251, v[84:85], off
	v_sub_co_u32_e32 v84, vcc, v2, v87
	s_movk_i32 s15, 0x2000
	s_nop 0
	v_subbrev_co_u32_e32 v85, vcc, 0, v3, vcc
	global_load_dword v252, v[84:85], off
	global_load_dword v249, v[2:3], off
	v_add_co_u32_e32 v84, vcc, s15, v2
	s_movk_i32 s15, 0x4000
	s_nop 0
	v_addc_co_u32_e32 v85, vcc, 0, v3, vcc
	global_load_dword v248, v[84:85], off
	v_add_co_u32_e32 v84, vcc, s15, v2
	s_movk_i32 s15, 0x6000
	s_nop 0
	v_addc_co_u32_e32 v85, vcc, 0, v3, vcc
	global_load_dword v247, v[84:85], off
	v_add_co_u32_e32 v84, vcc, s15, v2
	s_mov_b32 s15, 0x8000
	s_nop 0
	v_addc_co_u32_e32 v85, vcc, 0, v3, vcc
	global_load_dword v246, v[84:85], off
	v_add_co_u32_e32 v84, vcc, s15, v2
	s_mov_b32 s15, 0xa000
	s_nop 0
	v_addc_co_u32_e32 v85, vcc, 0, v3, vcc
	global_load_dword v245, v[84:85], off
	v_add_co_u32_e32 v84, vcc, s15, v2
	s_mov_b32 s15, 0xc000
	s_nop 0
	v_addc_co_u32_e32 v85, vcc, 0, v3, vcc
	global_load_dword v244, v[84:85], off
	v_add_co_u32_e32 v84, vcc, s15, v2
	s_mov_b32 s15, 0xe000
	s_nop 0
	v_addc_co_u32_e32 v85, vcc, 0, v3, vcc
	global_load_dword v243, v[84:85], off
	v_add_co_u32_e32 v84, vcc, s15, v2
	s_mov_b32 s15, 0x10000
	s_nop 0
	v_addc_co_u32_e32 v85, vcc, 0, v3, vcc
	global_load_dword v242, v[84:85], off
	v_add_co_u32_e32 v84, vcc, s15, v2
	s_mov_b32 s15, 0x12000
	s_nop 0
	v_addc_co_u32_e32 v85, vcc, 0, v3, vcc
	global_load_dword v241, v[84:85], off
	v_add_co_u32_e32 v84, vcc, s15, v2
	s_mov_b32 s15, 0x14000
	s_nop 0
	v_addc_co_u32_e32 v85, vcc, 0, v3, vcc
	global_load_dword v240, v[84:85], off
	v_add_co_u32_e32 v84, vcc, s15, v2
	s_mov_b32 s15, 0x16000
	s_nop 0
	v_addc_co_u32_e32 v85, vcc, 0, v3, vcc
	global_load_dword v239, v[84:85], off
	v_add_co_u32_e32 v84, vcc, s15, v2
	s_mov_b32 s15, 0x18000
	s_nop 0
	v_addc_co_u32_e32 v85, vcc, 0, v3, vcc
	global_load_dword v238, v[84:85], off
	v_add_co_u32_e32 v84, vcc, s15, v2
	s_mov_b32 s15, 0x1a000
	s_nop 0
	v_addc_co_u32_e32 v85, vcc, 0, v3, vcc
	v_add_co_u32_e32 v2, vcc, s15, v2
	global_load_dword v237, v[84:85], off
	s_nop 0
	v_addc_co_u32_e32 v3, vcc, 0, v3, vcc
	global_load_dword v236, v[2:3], off
	v_add_u32_e32 v2, s16, v159
	v_ashrrev_i32_e32 v3, 31, v2
	v_lshlrev_b64 v[2:3], 7, v[2:3]
	v_lshl_add_u64 v[2:3], s[90:91], 0, v[2:3]
	global_load_dword v153, v[2:3], off
	ds_read_b128 v[84:87], v180
	ds_read_b128 v[88:91], v181 offset:17408
	ds_read_b128 v[92:95], v181 offset:21760
	ds_read_b128 v[104:107], v180 offset:64
	ds_read_b128 v[96:99], v181 offset:17472
	ds_read_b128 v[100:103], v181 offset:21824
	ds_read_b128 v[108:111], v180 offset:128
	ds_read_b128 v[112:115], v181 offset:17536
	v_add_u32_e32 v192, v178, v228
	ds_read_b128 v[116:119], v181 offset:21888
	ds_read_b128 v[120:123], v180 offset:192
	s_waitcnt lgkmcnt(8)
	v_mfma_f32_16x16x32_bf16 v[88:91], v[84:87], v[88:91], 0
	ds_read_b128 v[124:127], v181 offset:17600
	s_waitcnt lgkmcnt(8)
	v_mfma_f32_16x16x32_bf16 v[84:87], v[84:87], v[92:95], 0
	ds_read_b128 v[128:131], v181 offset:21952
	s_waitcnt lgkmcnt(7)
	v_mfma_f32_16x16x32_bf16 v[88:91], v[104:107], v[96:99], v[88:91]
	s_waitcnt lgkmcnt(6)
	v_mfma_f32_16x16x32_bf16 v[84:87], v[104:107], v[100:103], v[84:87]
	s_waitcnt lgkmcnt(4)
	v_mfma_f32_16x16x32_bf16 v[88:91], v[108:111], v[112:115], v[88:91]
	s_waitcnt lgkmcnt(3)
	v_mfma_f32_16x16x32_bf16 v[84:87], v[108:111], v[116:119], v[84:87]
	s_waitcnt lgkmcnt(1)
	v_mfma_f32_16x16x32_bf16 v[88:91], v[120:123], v[124:127], v[88:91]
	s_waitcnt lgkmcnt(0)
	v_mfma_f32_16x16x32_bf16 v[84:87], v[120:123], v[128:131], v[84:87]
	s_nop 7
	ds_write2_b32 v202, v88, v84 offset1:16
	ds_write2_b32 v202, v89, v85 offset0:68 offset1:84
	ds_write2_b32 v202, v90, v86 offset0:136 offset1:152
	ds_write2_b32 v202, v91, v87 offset0:204 offset1:220
	ds_read2_b64 v[92:95], v224 offset1:4
	ds_read2_b64 v[100:103], v225 offset1:4
	ds_read2_b64 v[108:111], v226 offset1:4
	ds_read2_b64 v[116:119], v227 offset1:4
	ds_read2_b64 v[124:127], v224 offset0:8 offset1:12
	ds_read2_b64 v[128:131], v225 offset0:8 offset1:12
	ds_read2_b64 v[132:135], v226 offset0:8 offset1:12
	ds_read2_b64 v[136:139], v227 offset0:8 offset1:12
	v_cvt_pk_bf16_f32 v84, v4, v5
	v_cvt_pk_bf16_f32 v85, v6, v7
	v_cvt_pk_bf16_f32 v86, v12, v13
	v_cvt_pk_bf16_f32 v87, v14, v15
	v_cvt_pk_bf16_f32 v88, v8, v9
	v_cvt_pk_bf16_f32 v89, v10, v11
	v_cvt_pk_bf16_f32 v90, v16, v17
	v_cvt_pk_bf16_f32 v91, v18, v19
	ds_read2_b64 v[140:143], v224 offset0:16 offset1:20
	s_waitcnt lgkmcnt(8)
	v_mfma_f32_16x16x32_bf16 v[96:99], v[92:95], v[84:87], 0
	v_mfma_f32_16x16x32_bf16 v[92:95], v[92:95], v[88:91], 0
	ds_read2_b64 v[144:147], v225 offset0:16 offset1:20
	s_waitcnt lgkmcnt(8)
	v_mfma_f32_16x16x32_bf16 v[104:107], v[100:103], v[84:87], 0
	v_mfma_f32_16x16x32_bf16 v[100:103], v[100:103], v[88:91], 0
	s_waitcnt lgkmcnt(7)
	v_mfma_f32_16x16x32_bf16 v[112:115], v[108:111], v[84:87], 0
	v_mfma_f32_16x16x32_bf16 v[108:111], v[108:111], v[88:91], 0
	s_waitcnt lgkmcnt(6)
	v_mfma_f32_16x16x32_bf16 v[84:87], v[116:119], v[84:87], 0
	v_mfma_f32_16x16x32_bf16 v[88:91], v[116:119], v[88:91], 0
	v_cvt_pk_bf16_f32 v116, v20, v21
	v_cvt_pk_bf16_f32 v117, v22, v23
	v_cvt_pk_bf16_f32 v118, v28, v29
	v_cvt_pk_bf16_f32 v119, v30, v31
	v_cvt_pk_bf16_f32 v120, v24, v25
	v_cvt_pk_bf16_f32 v121, v26, v27
	v_cvt_pk_bf16_f32 v122, v32, v33
	v_cvt_pk_bf16_f32 v123, v34, v35
	s_waitcnt lgkmcnt(5)
	v_mfma_f32_16x16x32_bf16 v[96:99], v[124:127], v[116:119], v[96:99]
	v_mfma_f32_16x16x32_bf16 v[92:95], v[124:127], v[120:123], v[92:95]
	ds_read2_b64 v[124:127], v226 offset0:16 offset1:20
	s_waitcnt lgkmcnt(5)
	v_mfma_f32_16x16x32_bf16 v[104:107], v[128:131], v[116:119], v[104:107]
	v_mfma_f32_16x16x32_bf16 v[100:103], v[128:131], v[120:123], v[100:103]
	s_waitcnt lgkmcnt(4)
	v_mfma_f32_16x16x32_bf16 v[112:115], v[132:135], v[116:119], v[112:115]
	v_mfma_f32_16x16x32_bf16 v[108:111], v[132:135], v[120:123], v[108:111]
	s_waitcnt lgkmcnt(3)
	v_mfma_f32_16x16x32_bf16 v[84:87], v[136:139], v[116:119], v[84:87]
	v_cvt_pk_bf16_f32 v116, v36, v37
	v_cvt_pk_bf16_f32 v117, v38, v39
	v_cvt_pk_bf16_f32 v118, v44, v45
	v_mfma_f32_16x16x32_bf16 v[88:91], v[136:139], v[120:123], v[88:91]
	v_cvt_pk_bf16_f32 v119, v46, v47
	v_cvt_pk_bf16_f32 v120, v40, v41
	v_cvt_pk_bf16_f32 v121, v42, v43
	v_cvt_pk_bf16_f32 v122, v48, v49
	v_cvt_pk_bf16_f32 v123, v50, v51
	s_waitcnt lgkmcnt(2)
	v_mfma_f32_16x16x32_bf16 v[96:99], v[140:143], v[116:119], v[96:99]
	v_mfma_f32_16x16x32_bf16 v[92:95], v[140:143], v[120:123], v[92:95]
	s_waitcnt lgkmcnt(1)
	v_mfma_f32_16x16x32_bf16 v[104:107], v[144:147], v[116:119], v[104:107]
	v_mfma_f32_16x16x32_bf16 v[100:103], v[144:147], v[120:123], v[100:103]
	s_waitcnt lgkmcnt(0)
	v_mfma_f32_16x16x32_bf16 v[112:115], v[124:127], v[116:119], v[112:115]
	v_mfma_f32_16x16x32_bf16 v[108:111], v[124:127], v[120:123], v[108:111]
	ds_read2_b64 v[124:127], v227 offset0:16 offset1:20
	s_waitcnt lgkmcnt(0)
	v_mfma_f32_16x16x32_bf16 v[84:87], v[124:127], v[116:119], v[84:87]
	v_mfma_f32_16x16x32_bf16 v[116:119], v[124:127], v[120:123], v[88:91]
	ds_read2_b64 v[124:127], v224 offset0:24 offset1:28
	s_nop 1
	v_cvt_pk_bf16_f32 v88, v52, v53
	v_cvt_pk_bf16_f32 v89, v54, v55
	v_cvt_pk_bf16_f32 v90, v60, v61
	v_cvt_pk_bf16_f32 v91, v62, v63
	v_cvt_pk_bf16_f32 v120, v56, v57
	v_cvt_pk_bf16_f32 v121, v58, v59
	v_cvt_pk_bf16_f32 v122, v64, v65
	v_cvt_pk_bf16_f32 v123, v66, v67
	s_waitcnt lgkmcnt(0)
	v_mfma_f32_16x16x32_bf16 v[128:131], v[124:127], v[88:91], v[96:99]
	v_mfma_f32_16x16x32_bf16 v[124:127], v[124:127], v[120:123], v[92:95]
	s_nop 2
	ds_read2_b64 v[92:95], v225 offset0:24 offset1:28
	s_nop 2
	s_waitcnt lgkmcnt(0)
	v_mfma_f32_16x16x32_bf16 v[104:107], v[92:95], v[88:91], v[104:107]
	v_mfma_f32_16x16x32_bf16 v[132:135], v[92:95], v[120:123], v[100:103]
	ds_read2_b64 v[92:95], v226 offset0:24 offset1:28
	s_waitcnt lgkmcnt(0)
	v_mfma_f32_16x16x32_bf16 v[100:103], v[92:95], v[88:91], v[112:115]
	v_mfma_f32_16x16x32_bf16 v[96:99], v[92:95], v[120:123], v[108:111]
	ds_read2_b64 v[92:95], v227 offset0:24 offset1:28
	s_waitcnt lgkmcnt(0)
	v_mfma_f32_16x16x32_bf16 v[88:91], v[92:95], v[88:91], v[84:87]
	v_mfma_f32_16x16x32_bf16 v[92:95], v[92:95], v[120:123], v[116:119]
	v_add_u32_e32 v120, s33, v156
	s_nop 0
	ds_read_b128 v[84:87], v120
	ds_read_b128 v[136:139], v120 offset:64
	ds_read_b128 v[140:143], v120 offset:128
	s_nop 0
	s_waitcnt lgkmcnt(2)
	v_mul_f32_e32 v2, 0x3fb8aa3b, v84
	v_mul_f32_e32 v84, 0x3fb8aa3b, v86
	v_exp_f32_e32 v108, v84
	v_mul_f32_e32 v84, 0x3fb8aa3b, v87
	v_exp_f32_e32 v109, v84
	v_mul_f32_e32 v3, 0x3fb8aa3b, v85
	v_exp_f32_e32 v2, v2
	v_exp_f32_e32 v3, v3
	v_pk_mul_f32 v[86:87], v[130:131], v[108:109]
	v_pk_mul_f32 v[118:119], v[126:127], v[108:109]
	v_pk_mul_f32 v[84:85], v[128:129], v[2:3]
	v_pk_mul_f32 v[116:117], v[124:125], v[2:3]
	s_waitcnt lgkmcnt(1)
	v_mul_f32_e32 v2, 0x3fb8aa3b, v136
	v_mul_f32_e32 v108, 0x3fb8aa3b, v138
	v_mul_f32_e32 v3, 0x3fb8aa3b, v137
	v_exp_f32_e32 v112, v108
	v_mul_f32_e32 v108, 0x3fb8aa3b, v139
	v_exp_f32_e32 v2, v2
	v_exp_f32_e32 v3, v3
	v_exp_f32_e32 v113, v108
	v_pk_mul_f32 v[108:109], v[104:105], v[2:3]
	v_pk_mul_f32 v[110:111], v[106:107], v[112:113]
	v_pk_mul_f32 v[114:115], v[134:135], v[112:113]
	v_pk_mul_f32 v[112:113], v[132:133], v[2:3]
	s_waitcnt lgkmcnt(0)
	v_mul_f32_e32 v2, 0x3fb8aa3b, v140
	v_mul_f32_e32 v3, 0x3fb8aa3b, v141
	v_mul_f32_e32 v104, 0x3fb8aa3b, v142
	v_mul_f32_e32 v105, 0x3fb8aa3b, v143
	v_exp_f32_e32 v2, v2
	v_exp_f32_e32 v3, v3
	v_exp_f32_e32 v104, v104
	v_exp_f32_e32 v105, v105
	v_pk_mul_f32 v[100:101], v[100:101], v[2:3]
	v_pk_mul_f32 v[102:103], v[102:103], v[104:105]
	v_pk_mul_f32 v[106:107], v[98:99], v[104:105]
	v_pk_mul_f32 v[104:105], v[96:97], v[2:3]
	ds_read_b128 v[96:99], v120 offset:192
	s_waitcnt vmcnt(21)
	ds_write_b128 v230, v[76:79]
	s_waitcnt vmcnt(20)
	ds_write_b128 v230, v[80:83] offset:128
	s_waitcnt vmcnt(19)
	ds_write_b128 v230, v[72:75] offset:256
	s_waitcnt vmcnt(18)
	ds_write_b128 v230, v[68:71] offset:384
	s_waitcnt lgkmcnt(0)
	s_barrier
	v_mul_f32_e32 v2, 0x3fb8aa3b, v96
	v_mul_f32_e32 v3, 0x3fb8aa3b, v97
	v_mul_f32_e32 v96, 0x3fb8aa3b, v98
	v_mul_f32_e32 v97, 0x3fb8aa3b, v99
	v_exp_f32_e32 v2, v2
	v_exp_f32_e32 v3, v3
	v_exp_f32_e32 v96, v96
	v_exp_f32_e32 v97, v97
	v_pk_mul_f32 v[88:89], v[88:89], v[2:3]
	v_pk_mul_f32 v[90:91], v[90:91], v[96:97]
	v_pk_mul_f32 v[98:99], v[94:95], v[96:97]
	v_pk_mul_f32 v[96:97], v[92:93], v[2:3]
	v_mov_b32_e32 v2, s33
	ds_read_b32 v253, v2 offset:252
	ds_read_b128 v[148:151], v209
	ds_read_b128 v[140:143], v209 offset:16
	ds_read_b128 v[144:147], v201
	ds_read_b128 v[124:127], v201 offset:16
	ds_read_b128 v[120:123], v192 offset:53248
	s_waitcnt lgkmcnt(5)
	v_mul_f32_e32 v2, 0x3fb8aa3b, v253
	v_exp_f32_e32 v2, v2
	s_nop 0
	v_pk_mul_f32 v[6:7], v[6:7], v[2:3] op_sel_hi:[1,0]
	v_pk_mul_f32 v[4:5], v[4:5], v[2:3] op_sel_hi:[1,0]
	v_pk_mul_f32 v[74:75], v[10:11], v[2:3] op_sel_hi:[1,0]
	v_pk_mul_f32 v[72:73], v[8:9], v[2:3] op_sel_hi:[1,0]
	v_pk_mul_f32 v[10:11], v[14:15], v[2:3] op_sel_hi:[1,0]
	v_pk_mul_f32 v[8:9], v[12:13], v[2:3] op_sel_hi:[1,0]
	v_pk_mul_f32 v[18:19], v[18:19], v[2:3] op_sel_hi:[1,0]
	v_pk_mul_f32 v[16:17], v[16:17], v[2:3] op_sel_hi:[1,0]
	v_pk_mul_f32 v[14:15], v[22:23], v[2:3] op_sel_hi:[1,0]
	v_pk_mul_f32 v[12:13], v[20:21], v[2:3] op_sel_hi:[1,0]
	v_pk_mul_f32 v[26:27], v[26:27], v[2:3] op_sel_hi:[1,0]
	v_pk_mul_f32 v[24:25], v[24:25], v[2:3] op_sel_hi:[1,0]
	v_pk_mul_f32 v[22:23], v[30:31], v[2:3] op_sel_hi:[1,0]
	v_pk_mul_f32 v[20:21], v[28:29], v[2:3] op_sel_hi:[1,0]
	v_pk_mul_f32 v[34:35], v[34:35], v[2:3] op_sel_hi:[1,0]
	v_pk_mul_f32 v[32:33], v[32:33], v[2:3] op_sel_hi:[1,0]
	v_pk_mul_f32 v[30:31], v[38:39], v[2:3] op_sel_hi:[1,0]
	v_pk_mul_f32 v[28:29], v[36:37], v[2:3] op_sel_hi:[1,0]
	v_pk_mul_f32 v[42:43], v[42:43], v[2:3] op_sel_hi:[1,0]
	v_pk_mul_f32 v[40:41], v[40:41], v[2:3] op_sel_hi:[1,0]
	v_pk_mul_f32 v[38:39], v[46:47], v[2:3] op_sel_hi:[1,0]
	v_pk_mul_f32 v[36:37], v[44:45], v[2:3] op_sel_hi:[1,0]
	v_pk_mul_f32 v[50:51], v[50:51], v[2:3] op_sel_hi:[1,0]
	v_pk_mul_f32 v[48:49], v[48:49], v[2:3] op_sel_hi:[1,0]
	v_pk_mul_f32 v[46:47], v[54:55], v[2:3] op_sel_hi:[1,0]
	v_pk_mul_f32 v[44:45], v[52:53], v[2:3] op_sel_hi:[1,0]
	v_pk_mul_f32 v[58:59], v[58:59], v[2:3] op_sel_hi:[1,0]
	v_pk_mul_f32 v[56:57], v[56:57], v[2:3] op_sel_hi:[1,0]
	v_pk_mul_f32 v[54:55], v[62:63], v[2:3] op_sel_hi:[1,0]
	v_pk_mul_f32 v[52:53], v[60:61], v[2:3] op_sel_hi:[1,0]
	v_pk_mul_f32 v[62:63], v[66:67], v[2:3] op_sel_hi:[1,0]
	v_pk_mul_f32 v[60:61], v[64:65], v[2:3] op_sel_hi:[1,0]
	ds_read_b128 v[64:67], v192 offset:55552
	ds_read_b32 v2, v229
	ds_read_b128 v[68:71], v232
	ds_read_b128 v[76:79], v232 offset:16
	s_waitcnt lgkmcnt(2)
	v_sub_f32_e32 v3, v2, v148
	v_mul_f32_e32 v3, 0x3fb8aa3b, v3
	v_exp_f32_e32 v3, v3
	s_waitcnt lgkmcnt(1)
	v_mul_f32_e32 v3, v68, v3
	v_sub_f32_e32 v68, v2, v149
	v_mul_f32_e32 v68, 0x3fb8aa3b, v68
	v_exp_f32_e32 v68, v68
	v_mul_f32_e32 v3, v144, v3
	v_cndmask_b32_e64 v3, v3, 0, s[24:25]
	v_mul_f32_e32 v68, v69, v68
	v_sub_f32_e32 v69, v2, v150
	v_mul_f32_e32 v69, 0x3fb8aa3b, v69
	v_exp_f32_e32 v69, v69
	v_mul_f32_e32 v68, v145, v68
	v_cndmask_b32_e64 v68, 0, v68, s[26:27]
	ds_read_b32 v80, v229 offset:64
	ds_read_b128 v[128:131], v232 offset:4352
	ds_read_b128 v[132:135], v232 offset:4368
	v_cvt_pk_bf16_f32 v68, v3, v68
	v_mul_f32_e32 v69, v70, v69
	v_sub_f32_e32 v70, v2, v151
	v_mul_f32_e32 v70, 0x3fb8aa3b, v70
	v_exp_f32_e32 v70, v70
	v_mul_f32_e32 v69, v146, v69
	v_cndmask_b32_e64 v69, v69, 0, s[28:29]
	v_mul_f32_e32 v70, v71, v70
	v_sub_f32_e32 v71, v2, v140
	v_mul_f32_e32 v71, 0x3fb8aa3b, v71
	v_exp_f32_e32 v71, v71
	v_mul_f32_e32 v70, v147, v70
	v_cndmask_b32_e64 v70, v70, 0, s[30:31]
	v_cvt_pk_bf16_f32 v69, v69, v70
	s_waitcnt lgkmcnt(3)
	v_mul_f32_e32 v71, v76, v71
	v_sub_f32_e32 v76, v2, v141
	v_mul_f32_e32 v76, 0x3fb8aa3b, v76
	v_exp_f32_e32 v76, v76
	v_mul_f32_e32 v71, v124, v71
	v_cndmask_b32_e64 v71, v71, 0, s[34:35]
	v_mul_f32_e32 v76, v77, v76
	v_sub_f32_e32 v77, v2, v142
	v_sub_f32_e32 v2, v2, v143
	v_mul_f32_e32 v77, 0x3fb8aa3b, v77
	v_mul_f32_e32 v2, 0x3fb8aa3b, v2
	v_exp_f32_e32 v77, v77
	v_exp_f32_e32 v2, v2
	v_mul_f32_e32 v76, v125, v76
	v_cndmask_b32_e64 v76, v76, 0, s[36:37]
	v_mul_f32_e32 v77, v78, v77
	v_mul_f32_e32 v2, v79, v2
	v_mul_f32_e32 v77, v126, v77
	v_mul_f32_e32 v2, v127, v2
	v_cndmask_b32_e64 v77, v77, 0, s[38:39]
	v_cndmask_b32_e64 v2, v2, 0, s[40:41]
	v_cvt_pk_bf16_f32 v70, v71, v76
	v_cvt_pk_bf16_f32 v71, v77, v2
	s_nop 0
	s_nop 0
	v_mfma_f32_16x16x32_bf16 v[92:95], v[68:71], v[120:123], v[84:87]
	v_mfma_f32_16x16x32_bf16 v[84:87], v[68:71], v[64:67], v[116:119]
	s_waitcnt lgkmcnt(2)
	v_sub_f32_e32 v3, v80, v148
	v_mul_f32_e32 v3, 0x3fb8aa3b, v3
	v_exp_f32_e32 v3, v3
	s_waitcnt lgkmcnt(1)
	v_mul_f32_e32 v3, v128, v3
	v_sub_f32_e32 v68, v80, v149
	v_mul_f32_e32 v68, 0x3fb8aa3b, v68
	v_exp_f32_e32 v68, v68
	v_mul_f32_e32 v3, v144, v3
	v_cndmask_b32_e64 v3, v3, 0, s[42:43]
	v_mul_f32_e32 v68, v129, v68
	v_sub_f32_e32 v69, v80, v150
	v_mul_f32_e32 v69, 0x3fb8aa3b, v69
	v_exp_f32_e32 v69, v69
	v_mul_f32_e32 v68, v145, v68
	ds_read_b32 v116, v229 offset:128
	ds_read_b128 v[136:139], v232 offset:8704
	v_cndmask_b32_e64 v68, 0, v68, s[44:45]
	v_cvt_pk_bf16_f32 v68, v3, v68
	v_mul_f32_e32 v69, v130, v69
	v_sub_f32_e32 v70, v80, v151
	v_mul_f32_e32 v70, 0x3fb8aa3b, v70
	v_exp_f32_e32 v70, v70
	v_mul_f32_e32 v69, v146, v69
	v_cndmask_b32_e64 v69, v69, 0, s[46:47]
	v_mul_f32_e32 v70, v131, v70
	v_sub_f32_e32 v71, v80, v140
	v_mul_f32_e32 v71, 0x3fb8aa3b, v71
	v_exp_f32_e32 v71, v71
	v_mul_f32_e32 v70, v147, v70
	v_cndmask_b32_e64 v70, v70, 0, s[48:49]
	v_cvt_pk_bf16_f32 v69, v69, v70
	s_waitcnt lgkmcnt(2)
	v_mul_f32_e32 v71, v132, v71
	v_sub_f32_e32 v76, v80, v141
	v_mul_f32_e32 v76, 0x3fb8aa3b, v76
	v_exp_f32_e32 v76, v76
	v_mul_f32_e32 v71, v124, v71
	v_cndmask_b32_e64 v71, v71, 0, s[50:51]
	v_mul_f32_e32 v76, v133, v76
	v_sub_f32_e32 v77, v80, v142
	v_sub_f32_e32 v2, v80, v143
	v_mul_f32_e32 v77, 0x3fb8aa3b, v77
	v_mul_f32_e32 v2, 0x3fb8aa3b, v2
	v_exp_f32_e32 v77, v77
	v_exp_f32_e32 v2, v2
	v_mul_f32_e32 v76, v125, v76
	v_cndmask_b32_e64 v76, v76, 0, s[52:53]
	v_mul_f32_e32 v77, v134, v77
	v_mul_f32_e32 v2, v135, v2
	v_mul_f32_e32 v77, v126, v77
	v_mul_f32_e32 v2, v127, v2
	v_cndmask_b32_e64 v77, v77, 0, s[54:55]
	v_cndmask_b32_e64 v2, v2, 0, s[56:57]
	v_cvt_pk_bf16_f32 v70, v71, v76
	v_cvt_pk_bf16_f32 v71, v77, v2
	s_nop 0
	s_nop 0
	v_mfma_f32_16x16x32_bf16 v[76:79], v[68:71], v[120:123], v[108:111]
	s_nop 2
	ds_read_b128 v[108:111], v232 offset:8720
	s_nop 0
	s_waitcnt lgkmcnt(2)
	v_sub_f32_e32 v3, v116, v148
	v_mul_f32_e32 v3, 0x3fb8aa3b, v3
	v_exp_f32_e32 v3, v3
	v_mfma_f32_16x16x32_bf16 v[68:71], v[68:71], v[64:67], v[112:115]
	s_waitcnt lgkmcnt(1)
	v_mul_f32_e32 v3, v136, v3
	v_sub_f32_e32 v80, v116, v149
	v_mul_f32_e32 v80, 0x3fb8aa3b, v80
	v_exp_f32_e32 v80, v80
	ds_read_b32 v112, v229 offset:192
	ds_read_b128 v[128:131], v232 offset:13056
	v_mul_f32_e32 v3, v144, v3
	v_mul_f32_e32 v80, v137, v80
	v_sub_f32_e32 v81, v116, v150
	v_mul_f32_e32 v81, 0x3fb8aa3b, v81
	v_exp_f32_e32 v81, v81
	v_mul_f32_e32 v80, v145, v80
	v_cvt_pk_bf16_f32 v80, v3, v80
	v_mul_f32_e32 v81, v138, v81
	v_sub_f32_e32 v82, v116, v151
	v_mul_f32_e32 v82, 0x3fb8aa3b, v82
	v_exp_f32_e32 v82, v82
	v_mul_f32_e32 v81, v146, v81
	v_mul_f32_e32 v82, v139, v82
	v_sub_f32_e32 v83, v116, v140
	v_mul_f32_e32 v83, 0x3fb8aa3b, v83
	v_exp_f32_e32 v83, v83
	v_mul_f32_e32 v82, v147, v82
	v_cvt_pk_bf16_f32 v81, v81, v82
	s_waitcnt lgkmcnt(2)
	v_mul_f32_e32 v83, v108, v83
	v_sub_f32_e32 v108, v116, v141
	v_mul_f32_e32 v108, 0x3fb8aa3b, v108
	v_exp_f32_e32 v108, v108
	v_mul_f32_e32 v83, v124, v83
	v_mul_f32_e32 v108, v109, v108
	v_sub_f32_e32 v109, v116, v142
	v_sub_f32_e32 v2, v116, v143
	v_mul_f32_e32 v109, 0x3fb8aa3b, v109
	v_mul_f32_e32 v2, 0x3fb8aa3b, v2
	v_exp_f32_e32 v109, v109
	v_exp_f32_e32 v2, v2
	v_mul_f32_e32 v108, v125, v108
	v_cvt_pk_bf16_f32 v82, v83, v108
	v_mul_f32_e32 v109, v110, v109
	v_mul_f32_e32 v2, v111, v2
	v_mul_f32_e32 v109, v126, v109
	v_mul_f32_e32 v2, v127, v2
	v_cvt_pk_bf16_f32 v83, v109, v2
	s_nop 0
	s_nop 0
	v_mfma_f32_16x16x32_bf16 v[132:135], v[80:83], v[120:123], v[100:103]
	s_nop 2
	ds_read_b128 v[100:103], v232 offset:13072
	v_mfma_f32_16x16x32_bf16 v[136:139], v[80:83], v[64:67], v[104:107]
	s_waitcnt lgkmcnt(2)
	v_sub_f32_e32 v3, v112, v148
	v_mul_f32_e32 v3, 0x3fb8aa3b, v3
	v_exp_f32_e32 v3, v3
	s_waitcnt lgkmcnt(1)
	v_mul_f32_e32 v3, v128, v3
	v_sub_f32_e32 v80, v112, v149
	v_mul_f32_e32 v80, 0x3fb8aa3b, v80
	v_exp_f32_e32 v80, v80
	v_mul_f32_e32 v3, v144, v3
	v_mul_f32_e32 v80, v129, v80
	v_sub_f32_e32 v81, v112, v150
	v_mul_f32_e32 v81, 0x3fb8aa3b, v81
	v_exp_f32_e32 v81, v81
	v_mul_f32_e32 v80, v145, v80
	v_mul_f32_e32 v81, v130, v81
	v_sub_f32_e32 v82, v112, v151
	v_mul_f32_e32 v82, 0x3fb8aa3b, v82
	v_exp_f32_e32 v82, v82
	v_mul_f32_e32 v81, v146, v81
	v_mul_f32_e32 v82, v131, v82
	v_sub_f32_e32 v83, v112, v140
	v_mul_f32_e32 v83, 0x3fb8aa3b, v83
	v_exp_f32_e32 v83, v83
	v_mul_f32_e32 v82, v147, v82
	s_waitcnt lgkmcnt(0)
	v_mul_f32_e32 v83, v100, v83
	v_sub_f32_e32 v100, v112, v141
	v_mul_f32_e32 v100, 0x3fb8aa3b, v100
	v_exp_f32_e32 v100, v100
	v_mul_f32_e32 v83, v124, v83
	v_mul_f32_e32 v100, v101, v100
	v_mul_f32_e32 v104, v125, v100
	v_sub_f32_e32 v100, v112, v142
	v_sub_f32_e32 v2, v112, v143
	v_mul_f32_e32 v100, 0x3fb8aa3b, v100
	v_mul_f32_e32 v2, 0x3fb8aa3b, v2
	v_exp_f32_e32 v100, v100
	v_exp_f32_e32 v2, v2
	v_mul_f32_e32 v100, v102, v100
	v_mul_f32_e32 v2, v103, v2
	v_mul_f32_e32 v105, v126, v100
	v_mul_f32_e32 v2, v127, v2
	v_cvt_pk_bf16_f32 v100, v3, v80
	v_cvt_pk_bf16_f32 v101, v81, v82
	v_cvt_pk_bf16_f32 v102, v83, v104
	v_cvt_pk_bf16_f32 v103, v105, v2
	v_sub_f32_e32 v2, v253, v148
	s_nop 0
	v_mfma_f32_16x16x32_bf16 v[80:83], v[100:103], v[120:123], v[88:91]
	v_sub_f32_e32 v3, v253, v149
	v_mul_f32_e32 v2, 0x3fb8aa3b, v2
	v_mul_f32_e32 v3, 0x3fb8aa3b, v3
	v_sub_f32_e32 v88, v253, v150
	v_mul_f32_e32 v88, 0x3fb8aa3b, v88
	v_exp_f32_e32 v88, v88
	v_mfma_f32_16x16x32_bf16 v[128:131], v[100:103], v[64:67], v[96:99]
	v_exp_f32_e32 v2, v2
	v_exp_f32_e32 v3, v3
	v_and_b32_e32 v89, 0xffff0000, v120
	v_mul_f32_e32 v96, v146, v88
	v_sub_f32_e32 v88, v253, v151
	v_mul_f32_e32 v88, 0x3fb8aa3b, v88
	v_exp_f32_e32 v88, v88
	v_mul_f32_e32 v2, v144, v2
	v_mul_f32_e32 v3, v145, v3
	v_lshlrev_b32_e32 v90, 16, v121
	v_mul_f32_e32 v97, v147, v88
	v_sub_f32_e32 v88, v253, v140
	v_mul_f32_e32 v88, 0x3fb8aa3b, v88
	v_exp_f32_e32 v88, v88
	v_lshlrev_b32_e32 v102, 16, v122
	v_mul_f32_e32 v89, v3, v89
	v_mul_f32_e32 v90, v96, v90
	v_mul_f32_e32 v98, v124, v88
	v_sub_f32_e32 v88, v253, v141
	v_mul_f32_e32 v88, 0x3fb8aa3b, v88
	v_exp_f32_e32 v88, v88
	v_and_b32_e32 v91, 0xffff0000, v121
	v_mul_f32_e32 v102, v98, v102
	v_and_b32_e32 v103, 0xffff0000, v122
	v_mul_f32_e32 v99, v125, v88
	ds_read_b128 v[106:109], v233 offset:34816
	v_sub_f32_e32 v88, v253, v142
	v_mul_f32_e32 v88, 0x3fb8aa3b, v88
	ds_read_b128 v[110:113], v233 offset:37120
	v_exp_f32_e32 v88, v88
	v_mul_f32_e32 v91, v97, v91
	ds_read_b128 v[114:117], v233 offset:39424
	v_mul_f32_e32 v103, v99, v103
	v_lshlrev_b32_e32 v104, 16, v123
	ds_read_b128 v[144:147], v233 offset:41728
	v_mul_f32_e32 v100, v126, v88
	v_sub_f32_e32 v88, v253, v143
	ds_read_b128 v[148:151], v233 offset:44032
	v_mul_f32_e32 v88, 0x3fb8aa3b, v88
	v_exp_f32_e32 v88, v88
	v_and_b32_e32 v105, 0xffff0000, v123
	v_mul_f32_e32 v104, v100, v104
	v_mul_f32_e32 v101, v127, v88
	v_lshlrev_b32_e32 v88, 16, v120
	v_mul_f32_e32 v88, v2, v88
	v_cvt_pk_bf16_f32 v88, v88, v89
	v_cvt_pk_bf16_f32 v89, v90, v91
	v_cvt_pk_bf16_f32 v90, v102, v103
	v_lshlrev_b32_e32 v102, 16, v64
	v_and_b32_e32 v64, 0xffff0000, v64
	v_mul_f32_e32 v3, v3, v64
	v_lshlrev_b32_e32 v64, 16, v65
	v_mul_f32_e32 v64, v96, v64
	v_lshlrev_b32_e32 v96, 16, v66
	v_and_b32_e32 v65, 0xffff0000, v65
	v_mul_f32_e32 v98, v98, v96
	v_and_b32_e32 v66, 0xffff0000, v66
	v_lshlrev_b32_e32 v96, 16, v67
	v_and_b32_e32 v67, 0xffff0000, v67
	v_mul_f32_e32 v65, v97, v65
	v_mul_f32_e32 v66, v99, v66
	v_mul_f32_e32 v99, v100, v96
	v_mul_f32_e32 v67, v101, v67
	v_mul_f32_e32 v105, v101, v105
	v_cvt_pk_bf16_f32 v91, v104, v105
	v_mul_f32_e32 v2, v2, v102
	v_cvt_pk_bf16_f32 v96, v2, v3
	v_cvt_pk_bf16_f32 v97, v64, v65
	v_cvt_pk_bf16_f32 v98, v98, v66
	v_cvt_pk_bf16_f32 v99, v99, v67
	s_waitcnt lgkmcnt(4)
	v_mfma_f32_16x16x32_bf16 v[2:5], v[106:109], v[88:91], v[4:7]
	v_mfma_f32_16x16x32_bf16 v[140:143], v[106:109], v[96:99], v[72:75]
	s_waitcnt lgkmcnt(3)
	v_mfma_f32_16x16x32_bf16 v[120:123], v[110:113], v[88:91], v[8:11]
	s_nop 2
	ds_read_b128 v[6:9], v233 offset:46336
	s_nop 2
	s_waitcnt lgkmcnt(3)
	v_mfma_f32_16x16x32_bf16 v[124:127], v[114:117], v[88:91], v[12:15]
	v_mfma_f32_16x16x32_bf16 v[24:27], v[114:117], v[96:99], v[24:27]
	s_waitcnt lgkmcnt(2)
	v_mfma_f32_16x16x32_bf16 v[116:119], v[144:147], v[88:91], v[20:23]
	v_mfma_f32_16x16x32_bf16 v[32:35], v[144:147], v[96:99], v[32:35]
	v_mfma_f32_16x16x32_bf16 v[16:19], v[110:113], v[96:99], v[16:19]
	s_waitcnt lgkmcnt(1)
	v_mfma_f32_16x16x32_bf16 v[64:67], v[148:151], v[88:91], v[28:31]
	v_mfma_f32_16x16x32_bf16 v[40:43], v[148:151], v[96:99], v[40:43]
	s_waitcnt lgkmcnt(0)
	v_mfma_f32_16x16x32_bf16 v[100:103], v[6:9], v[88:91], v[36:39]
	v_mfma_f32_16x16x32_bf16 v[48:51], v[6:9], v[96:99], v[48:51]
	ds_read_b128 v[6:9], v233 offset:48640
	s_waitcnt lgkmcnt(0)
	v_mfma_f32_16x16x32_bf16 v[104:107], v[6:9], v[88:91], v[44:47]
	v_mfma_f32_16x16x32_bf16 v[56:59], v[6:9], v[96:99], v[56:59]
	ds_read_b128 v[6:9], v233 offset:50944
	s_nop 0
	ds_read_b128 v[44:47], v209 offset:128
	ds_read_b128 v[28:31], v209 offset:144
	ds_read_b128 v[36:39], v201 offset:128
	ds_read_b128 v[20:23], v201 offset:144
	ds_read_b128 v[10:13], v192 offset:53312
	s_waitcnt lgkmcnt(5)
	v_mfma_f32_16x16x32_bf16 v[108:111], v[6:9], v[88:91], v[52:55]
	v_mfma_f32_16x16x32_bf16 v[112:115], v[6:9], v[96:99], v[60:63]
	ds_read_b128 v[6:9], v192 offset:55616
	ds_read_b32 v14, v229 offset:128
	ds_read_b128 v[52:55], v232 offset:8832
	ds_read_b128 v[60:63], v232 offset:8848
	s_waitcnt lgkmcnt(2)
	v_sub_f32_e32 v15, v14, v44
	v_mul_f32_e32 v15, 0x3fb8aa3b, v15
	v_exp_f32_e32 v15, v15
	s_waitcnt lgkmcnt(1)
	v_mul_f32_e32 v15, v52, v15
	v_sub_f32_e32 v52, v14, v45
	v_mul_f32_e32 v52, 0x3fb8aa3b, v52
	v_exp_f32_e32 v52, v52
	v_mul_f32_e32 v15, v36, v15
	v_cndmask_b32_e64 v15, v15, 0, s[24:25]
	v_mul_f32_e32 v52, v53, v52
	v_sub_f32_e32 v53, v14, v46
	v_mul_f32_e32 v53, 0x3fb8aa3b, v53
	v_exp_f32_e32 v53, v53
	v_mul_f32_e32 v52, v37, v52
	v_cndmask_b32_e64 v52, v52, 0, s[58:59]
	ds_read_b32 v72, v229 offset:192
	ds_read_b128 v[144:147], v232 offset:13184
	ds_read_b128 v[148:151], v232 offset:13200
	v_cvt_pk_bf16_f32 v52, v15, v52
	v_mul_f32_e32 v53, v54, v53
	v_sub_f32_e32 v54, v14, v47
	v_mul_f32_e32 v54, 0x3fb8aa3b, v54
	v_exp_f32_e32 v54, v54
	v_mul_f32_e32 v53, v38, v53
	v_cndmask_b32_e64 v53, v53, 0, s[60:61]
	v_mul_f32_e32 v54, v55, v54
	v_sub_f32_e32 v55, v14, v28
	v_mul_f32_e32 v55, 0x3fb8aa3b, v55
	v_exp_f32_e32 v55, v55
	v_mul_f32_e32 v54, v39, v54
	v_cndmask_b32_e64 v54, v54, 0, s[62:63]
	v_cvt_pk_bf16_f32 v53, v53, v54
	s_waitcnt lgkmcnt(3)
	v_mul_f32_e32 v55, v60, v55
	v_sub_f32_e32 v60, v14, v29
	v_mul_f32_e32 v60, 0x3fb8aa3b, v60
	v_exp_f32_e32 v60, v60
	v_mul_f32_e32 v55, v20, v55
	v_cndmask_b32_e64 v55, v55, 0, s[64:65]
	v_mul_f32_e32 v60, v61, v60
	v_sub_f32_e32 v61, v14, v30
	v_sub_f32_e32 v14, v14, v31
	v_mul_f32_e32 v61, 0x3fb8aa3b, v61
	v_mul_f32_e32 v14, 0x3fb8aa3b, v14
	v_exp_f32_e32 v61, v61
	v_exp_f32_e32 v14, v14
	v_mul_f32_e32 v60, v21, v60
	v_cndmask_b32_e64 v60, v60, 0, s[66:67]
	v_mul_f32_e32 v61, v62, v61
	v_mul_f32_e32 v14, v63, v14
	v_mul_f32_e32 v61, v22, v61
	v_mul_f32_e32 v14, v23, v14
	v_cndmask_b32_e64 v61, v61, 0, s[68:69]
	v_cndmask_b32_e64 v14, v14, 0, s[70:71]
	v_cvt_pk_bf16_f32 v54, v55, v60
	v_cvt_pk_bf16_f32 v55, v61, v14
	s_nop 0
	s_nop 0
	v_mfma_f32_16x16x32_bf16 v[96:99], v[52:55], v[10:13], v[132:135]
	v_mfma_f32_16x16x32_bf16 v[88:91], v[52:55], v[6:9], v[136:139]
	s_waitcnt lgkmcnt(2)
	v_sub_f32_e32 v15, v72, v44
	v_mul_f32_e32 v15, 0x3fb8aa3b, v15
	v_exp_f32_e32 v15, v15
	s_waitcnt lgkmcnt(1)
	v_mul_f32_e32 v15, v144, v15
	v_sub_f32_e32 v52, v72, v45
	v_mul_f32_e32 v52, 0x3fb8aa3b, v52
	v_exp_f32_e32 v52, v52
	v_mul_f32_e32 v15, v36, v15
	v_cndmask_b32_e64 v15, v15, 0, s[72:73]
	v_mul_f32_e32 v52, v145, v52
	v_sub_f32_e32 v53, v72, v46
	v_mul_f32_e32 v53, 0x3fb8aa3b, v53
	v_exp_f32_e32 v53, v53
	v_mul_f32_e32 v52, v37, v52
	v_cndmask_b32_e64 v52, v52, 0, s[74:75]
	v_cvt_pk_bf16_f32 v52, v15, v52
	v_mul_f32_e32 v53, v146, v53
	v_sub_f32_e32 v54, v72, v47
	v_mul_f32_e32 v54, 0x3fb8aa3b, v54
	v_exp_f32_e32 v54, v54
	v_mul_f32_e32 v53, v38, v53
	v_cndmask_b32_e64 v53, v53, 0, s[76:77]
	v_sub_f32_e32 v15, v253, v45
	v_mul_f32_e32 v54, v147, v54
	v_sub_f32_e32 v55, v72, v28
	v_mul_f32_e32 v55, 0x3fb8aa3b, v55
	v_exp_f32_e32 v55, v55
	v_sub_f32_e32 v28, v253, v28
	v_mul_f32_e32 v28, 0x3fb8aa3b, v28
	v_exp_f32_e32 v28, v28
	s_waitcnt lgkmcnt(0)
	v_mul_f32_e32 v55, v148, v55
	v_sub_f32_e32 v60, v72, v29
	v_mul_f32_e32 v60, 0x3fb8aa3b, v60
	v_exp_f32_e32 v60, v60
	v_mul_f32_e32 v55, v20, v55
	v_mul_f32_e32 v20, v20, v28
	v_sub_f32_e32 v28, v253, v29
	v_mul_f32_e32 v60, v149, v60
	v_sub_f32_e32 v61, v72, v30
	v_sub_f32_e32 v14, v72, v31
	v_mul_f32_e32 v14, 0x3fb8aa3b, v14
	v_mul_f32_e32 v61, 0x3fb8aa3b, v61
	v_exp_f32_e32 v14, v14
	v_exp_f32_e32 v61, v61
	v_mul_f32_e32 v28, 0x3fb8aa3b, v28
	v_exp_f32_e32 v28, v28
	v_mul_f32_e32 v14, v151, v14
	v_mul_f32_e32 v54, v39, v54
	v_mul_f32_e32 v61, v150, v61
	v_mul_f32_e32 v14, v23, v14
	v_cndmask_b32_e64 v54, v54, 0, s[78:79]
	v_cndmask_b32_e64 v55, v55, 0, s[80:81]
	v_mul_f32_e32 v60, v21, v60
	v_mul_f32_e32 v61, v22, v61
	v_cndmask_b32_e64 v14, v14, 0, s[86:87]
	v_mul_f32_e32 v21, v21, v28
	v_sub_f32_e32 v28, v253, v30
	v_cndmask_b32_e64 v60, v60, 0, s[82:83]
	v_cndmask_b32_e64 v61, v61, 0, s[84:85]
	v_cvt_pk_bf16_f32 v53, v53, v54
	v_cvt_pk_bf16_f32 v54, v55, v60
	v_cvt_pk_bf16_f32 v55, v61, v14
	v_sub_f32_e32 v14, v253, v44
	v_mul_f32_e32 v15, 0x3fb8aa3b, v15
	v_mul_f32_e32 v28, 0x3fb8aa3b, v28
	v_mul_f32_e32 v14, 0x3fb8aa3b, v14
	v_exp_f32_e32 v15, v15
	v_exp_f32_e32 v28, v28
	v_exp_f32_e32 v14, v14
	v_mfma_f32_16x16x32_bf16 v[80:83], v[52:55], v[10:13], v[80:83]
	v_mul_f32_e32 v15, v37, v15
	v_sub_f32_e32 v37, v253, v47
	v_mul_f32_e32 v22, v22, v28
	v_sub_f32_e32 v28, v253, v31
	v_mul_f32_e32 v14, v36, v14
	v_sub_f32_e32 v36, v253, v46
	v_mul_f32_e32 v37, 0x3fb8aa3b, v37
	v_mul_f32_e32 v28, 0x3fb8aa3b, v28
	v_mul_f32_e32 v36, 0x3fb8aa3b, v36
	v_exp_f32_e32 v37, v37
	v_exp_f32_e32 v28, v28
	v_exp_f32_e32 v36, v36
	v_lshlrev_b32_e32 v29, 16, v11
	v_mul_f32_e32 v37, v39, v37
	v_mul_f32_e32 v23, v23, v28
	v_lshlrev_b32_e32 v28, 16, v10
	ds_read_b128 v[132:135], v233 offset:34880
	ds_read_b128 v[136:139], v233 offset:37184
	ds_read_b128 v[144:147], v233 offset:39488
	ds_read_b128 v[148:151], v233 offset:41792
	ds_read_b128 v[44:47], v233 offset:44096
	v_and_b32_e32 v10, 0xffff0000, v10
	v_and_b32_e32 v11, 0xffff0000, v11
	v_lshlrev_b32_e32 v30, 16, v12
	v_and_b32_e32 v12, 0xffff0000, v12
	v_lshlrev_b32_e32 v31, 16, v13
	v_and_b32_e32 v13, 0xffff0000, v13
	v_mul_f32_e32 v36, v38, v36
	v_mul_f32_e32 v10, v15, v10
	v_mul_f32_e32 v11, v37, v11
	v_mul_f32_e32 v12, v21, v12
	v_mul_f32_e32 v13, v23, v13
	v_mfma_f32_16x16x32_bf16 v[72:75], v[52:55], v[6:9], v[128:131]
	ds_read_b128 v[52:55], v233 offset:46400
	v_mul_f32_e32 v28, v14, v28
	v_mul_f32_e32 v29, v36, v29
	v_mul_f32_e32 v30, v20, v30
	v_mul_f32_e32 v31, v22, v31
	v_cvt_pk_bf16_f32 v60, v28, v10
	v_cvt_pk_bf16_f32 v61, v29, v11
	v_cvt_pk_bf16_f32 v62, v30, v12
	v_cvt_pk_bf16_f32 v63, v31, v13
	v_lshlrev_b32_e32 v10, 16, v6
	v_lshlrev_b32_e32 v11, 16, v7
	v_lshlrev_b32_e32 v12, 16, v8
	v_and_b32_e32 v8, 0xffff0000, v8
	v_lshlrev_b32_e32 v13, 16, v9
	v_and_b32_e32 v9, 0xffff0000, v9
	v_mul_f32_e32 v10, v14, v10
	v_and_b32_e32 v6, 0xffff0000, v6
	v_mul_f32_e32 v11, v36, v11
	v_and_b32_e32 v7, 0xffff0000, v7
	v_mul_f32_e32 v8, v21, v8
	v_mul_f32_e32 v9, v23, v9
	v_mul_f32_e32 v6, v15, v6
	v_mul_f32_e32 v7, v37, v7
	v_mul_f32_e32 v12, v20, v12
	v_mul_f32_e32 v13, v22, v13
	v_cvt_pk_bf16_f32 v128, v10, v6
	v_cvt_pk_bf16_f32 v129, v11, v7
	v_cvt_pk_bf16_f32 v130, v12, v8
	v_cvt_pk_bf16_f32 v131, v13, v9
	s_waitcnt lgkmcnt(4)
	v_mfma_f32_16x16x32_bf16 v[12:15], v[136:139], v[60:63], v[120:123]
	v_mfma_f32_16x16x32_bf16 v[16:19], v[136:139], v[128:131], v[16:19]
	s_waitcnt lgkmcnt(3)
	v_mfma_f32_16x16x32_bf16 v[20:23], v[144:147], v[60:63], v[124:127]
	v_mfma_f32_16x16x32_bf16 v[24:27], v[144:147], v[128:131], v[24:27]
	s_waitcnt lgkmcnt(2)
	v_mfma_f32_16x16x32_bf16 v[28:31], v[148:151], v[60:63], v[116:119]
	v_mfma_f32_16x16x32_bf16 v[32:35], v[148:151], v[128:131], v[32:35]
	s_waitcnt lgkmcnt(1)
	v_mfma_f32_16x16x32_bf16 v[36:39], v[44:47], v[60:63], v[64:67]
	s_nop 2
	ds_read_b128 v[64:67], v233 offset:48704
	s_nop 2
	v_mfma_f32_16x16x32_bf16 v[4:7], v[132:135], v[60:63], v[2:5]
	s_nop 2
	ds_read_b64 v[2:3], v234 offset:53248
	ds_read_u16 v192, v235
	v_mfma_f32_16x16x32_bf16 v[40:43], v[44:47], v[128:131], v[40:43]
	s_nop 1
	s_waitcnt lgkmcnt(3)
	v_mfma_f32_16x16x32_bf16 v[44:47], v[52:55], v[60:63], v[100:103]
	s_nop 2
	ds_read_u16 v103, v235 offset:528
	v_mfma_f32_16x16x32_bf16 v[48:51], v[52:55], v[128:131], v[48:51]
	s_nop 1
	s_waitcnt lgkmcnt(2)
	v_lshlrev_b32_e32 v100, 16, v2
	v_mfma_f32_16x16x32_bf16 v[52:55], v[64:67], v[60:63], v[104:107]
	v_and_b32_e32 v101, 0xffff0000, v2
	s_waitcnt lgkmcnt(1)
	v_lshlrev_b32_e32 v102, 16, v192
	s_waitcnt lgkmcnt(0)
	v_lshlrev_b32_e32 v103, 16, v103
	v_mfma_f32_16x16x32_bf16 v[56:59], v[64:67], v[128:131], v[56:59]
	ds_read_b128 v[64:67], v233 offset:51008
	ds_read_u16 v116, v235 offset:1056
	ds_read_u16 v117, v235 offset:1584
	ds_read_b64 v[104:105], v234 offset:55552
	ds_read_u16 v106, v235 offset:32
	ds_read_u16 v107, v235 offset:560
	v_pk_fma_f32 v[92:93], v[154:155], v[100:101], v[92:93]
	v_pk_mul_f32 v[100:101], v[102:103], s[96:97] op_sel_hi:[1,0]
	v_lshlrev_b32_e32 v2, 16, v3
	v_exp_f32_e32 v100, v100
	v_exp_f32_e32 v101, v101
	v_and_b32_e32 v3, 0xffff0000, v3
	v_pk_fma_f32 v[2:3], v[154:155], v[2:3], v[94:95]
	v_mfma_f32_16x16x32_bf16 v[8:11], v[132:135], v[128:131], v[140:143]
	v_add_f32_e64 v100, v100, 1.0
	v_add_f32_e64 v101, v101, 1.0
	v_rcp_f32_e32 v100, v100
	v_rcp_f32_e32 v101, v101
	s_waitcnt lgkmcnt(5)
	v_mfma_f32_16x16x32_bf16 v[60:63], v[64:67], v[60:63], v[108:111]
	v_mul_f32_e64 v100, v100, v102
	v_mul_f32_e64 v101, v101, v103
	v_pk_mul_f32 v[92:93], v[92:93], v[100:101]
	v_mfma_f32_16x16x32_bf16 v[64:67], v[64:67], v[128:131], v[112:115]
	v_cvt_pk_bf16_f32 v102, v92, v93
	ds_write_b16 v235, v102
	ds_write_b16_d16_hi v235, v102 offset:528
	s_waitcnt lgkmcnt(6)
	v_lshlrev_b32_e32 v92, 16, v116
	s_waitcnt lgkmcnt(5)
	v_lshlrev_b32_e32 v93, 16, v117
	ds_read_u16 v100, v235 offset:1088
	ds_read_u16 v101, v235 offset:1616
	v_pk_mul_f32 v[94:95], v[92:93], s[96:97] op_sel_hi:[1,0]
	s_nop 0
	v_exp_f32_e32 v94, v94
	v_exp_f32_e32 v95, v95
	s_nop 0
	v_pk_add_f32 v[94:95], v[94:95], 1.0 op_sel_hi:[1,0]
	s_nop 0
	v_rcp_f32_e32 v94, v94
	v_rcp_f32_e32 v95, v95
	s_nop 0
	v_pk_mul_f32 v[92:93], v[94:95], v[92:93]
	s_nop 0
	v_pk_mul_f32 v[2:3], v[2:3], v[92:93]
	s_nop 0
	v_cvt_pk_bf16_f32 v103, v2, v3
	ds_write_b16 v235, v103 offset:1056
	ds_write_b16_d16_hi v235, v103 offset:1584
	s_waitcnt lgkmcnt(8)
	v_lshlrev_b32_e32 v92, 16, v104
	v_and_b32_e32 v93, 0xffff0000, v104
	s_waitcnt lgkmcnt(7)
	v_lshlrev_b32_e32 v94, 16, v106
	s_waitcnt lgkmcnt(6)
	v_lshlrev_b32_e32 v95, 16, v107
	v_pk_fma_f32 v[84:85], v[154:155], v[92:93], v[84:85]
	v_pk_mul_f32 v[92:93], v[94:95], s[96:97] op_sel_hi:[1,0]
	v_lshlrev_b32_e32 v2, 16, v105
	v_exp_f32_e32 v92, v92
	v_exp_f32_e32 v93, v93
	v_and_b32_e32 v3, 0xffff0000, v105
	v_pk_fma_f32 v[2:3], v[154:155], v[2:3], v[86:87]
	v_pk_add_f32 v[92:93], v[92:93], 1.0 op_sel_hi:[1,0]
	s_nop 0
	v_rcp_f32_e32 v92, v92
	v_rcp_f32_e32 v93, v93
	s_nop 0
	v_pk_mul_f32 v[92:93], v[92:93], v[94:95]
	s_nop 0
	v_pk_mul_f32 v[84:85], v[84:85], v[92:93]
	s_nop 0
	v_cvt_pk_bf16_f32 v92, v84, v85
	ds_write_b16 v235, v92 offset:32
	ds_write_b16_d16_hi v235, v92 offset:560
	s_waitcnt lgkmcnt(5)
	v_lshlrev_b32_e32 v84, 16, v100
	s_waitcnt lgkmcnt(4)
	v_lshlrev_b32_e32 v85, 16, v101
	v_pk_mul_f32 v[86:87], v[84:85], s[96:97] op_sel_hi:[1,0]
	s_nop 0
	v_exp_f32_e32 v86, v86
	v_exp_f32_e32 v87, v87
	s_nop 0
	v_pk_add_f32 v[86:87], v[86:87], 1.0 op_sel_hi:[1,0]
	s_nop 0
	v_rcp_f32_e32 v86, v86
	v_rcp_f32_e32 v87, v87
	s_nop 0
	v_pk_mul_f32 v[84:85], v[86:87], v[84:85]
	s_nop 0
	v_pk_mul_f32 v[2:3], v[2:3], v[84:85]
	v_lshlrev_b32_e32 v84, 16, v92
	v_cvt_pk_bf16_f32 v93, v2, v3
	v_and_b32_e32 v3, 64, v199
	v_xor_b32_e32 v2, 1, v199
	v_add_u32_e32 v3, 64, v3
	v_cmp_lt_i32_e32 vcc, v2, v3
	ds_write_b16 v235, v93 offset:1088
	ds_write_b16_d16_hi v235, v93 offset:1616
	v_cndmask_b32_e32 v2, v199, v2, vcc
	v_lshlrev_b32_e32 v101, 2, v2
	v_xor_b32_e32 v2, 2, v199
	v_cmp_lt_i32_e32 vcc, v2, v3
	v_and_b32_e32 v85, 0xffff0000, v92
	v_lshlrev_b32_e32 v92, 16, v93
	v_cndmask_b32_e32 v2, v199, v2, vcc
	v_lshlrev_b32_e32 v100, 2, v2
	v_xor_b32_e32 v2, 4, v199
	v_cmp_lt_i32_e32 vcc, v2, v3
	v_and_b32_e32 v93, 0xffff0000, v93
	v_pk_mul_f32 v[84:85], v[84:85], v[84:85]
	v_cndmask_b32_e32 v2, v199, v2, vcc
	v_lshlrev_b32_e32 v95, 2, v2
	v_xor_b32_e32 v2, 8, v199
	v_cmp_lt_i32_e32 vcc, v2, v3
	v_and_b32_e32 v3, 0xffff0000, v102
	v_lshlrev_b32_e32 v86, 16, v103
	v_cndmask_b32_e32 v2, v199, v2, vcc
	v_lshlrev_b32_e32 v94, 2, v2
	v_lshlrev_b32_e32 v2, 16, v102
	v_and_b32_e32 v87, 0xffff0000, v103
	v_pk_mul_f32 v[92:93], v[92:93], v[92:93]
	v_pk_fma_f32 v[2:3], v[2:3], v[2:3], v[84:85]
	v_pk_fma_f32 v[86:87], v[86:87], v[86:87], v[92:93]
	s_nop 0
	v_add_u32_e32 v102, s12, v156
	v_add_f32_dpp v2, v2, v2 quad_perm:[1,0,3,2] row_mask:0xf bank_mask:0xf
	v_add_f32_dpp v3, v3, v3 quad_perm:[1,0,3,2] row_mask:0xf bank_mask:0xf
	v_add_f32_dpp v86, v86, v86 quad_perm:[1,0,3,2] row_mask:0xf bank_mask:0xf
	v_add_f32_dpp v87, v87, v87 quad_perm:[1,0,3,2] row_mask:0xf bank_mask:0xf
	v_add_f32_dpp v2, v2, v2 quad_perm:[2,3,0,1] row_mask:0xf bank_mask:0xf
	v_add_f32_dpp v3, v3, v3 quad_perm:[2,3,0,1] row_mask:0xf bank_mask:0xf
	v_add_f32_dpp v86, v86, v86 quad_perm:[2,3,0,1] row_mask:0xf bank_mask:0xf
	v_add_f32_dpp v87, v87, v87 quad_perm:[2,3,0,1] row_mask:0xf bank_mask:0xf
	v_add_f32_dpp v2, v2, v2 row_half_mirror row_mask:0xf bank_mask:0xf
	v_add_f32_dpp v3, v3, v3 row_half_mirror row_mask:0xf bank_mask:0xf
	v_add_f32_dpp v86, v86, v86 row_half_mirror row_mask:0xf bank_mask:0xf
	v_add_f32_dpp v87, v87, v87 row_half_mirror row_mask:0xf bank_mask:0xf
	v_add_f32_dpp v84, v2, v2 row_mirror row_mask:0xf bank_mask:0xf
	v_add_f32_dpp v85, v3, v3 row_mirror row_mask:0xf bank_mask:0xf
	v_add_f32_dpp v86, v86, v86 row_mirror row_mask:0xf bank_mask:0xf
	v_add_f32_dpp v87, v87, v87 row_mirror row_mask:0xf bank_mask:0xf
	s_and_saveexec_b64 s[94:95], s[10:11]
	s_cbranch_execz .LBB0_382
	ds_write_b128 v102, v[84:87]
